# adds: P2 work-queue dequeue atomic left in flight during the item (result read at the next loop top) instead of waiting for it before the item starts
# baseline (speedup 1.0000x reference)
.LBB0_573:
	s_or_b64 exec, exec, s[6:7]
	s_waitcnt vmcnt(0)
	v_readfirstlane_b32 s0, v1
	s_nop 1
	v_add_u32_e32 v152, s0, v0
	v_mov_b32_e32 v253, v152

.LBB0_576:
	s_barrier
	s_mov_b64 s[4:5], exec
	v_readlane_b32 s0, v254, 7
	v_readlane_b32 s1, v254, 8
	s_and_b64 s[0:1], s[4:5], s[0:1]
	s_mov_b64 exec, s[0:1]
	s_cbranch_execz .Lq_nowq
	s_waitcnt vmcnt(0)
	v_mov_b32_e32 v152, v253
	v_mov_b32_e32 v0, s76
	ds_write_b32 v0, v152
.Lq_nowq:
	s_or_b64 exec, exec, s[4:5]
	s_waitcnt lgkmcnt(0)
	s_barrier
	ds_read_b32 v0, v154
	s_movk_i32 s0, 0x9ff
	s_waitcnt lgkmcnt(0)
	v_cmp_lt_i32_e64 s[4:5], s0, v0
	v_readfirstlane_b32 s89, v0
	s_and_b64 vcc, exec, s[4:5]
	s_cbranch_vccnz .LBB0_575
	s_cmpk_lt_i32 s89, 0x80
	s_cbranch_scc1 .Lq_done
	s_sub_i32 s0, s89, 0x80
	s_cmpk_lt_i32 s0, 0x540
	s_cbranch_scc0 .Lq_r2
	s_mul_i32 s1, s0, 0x124a
	s_lshr_b32 s1, s1, 16
	s_mul_i32 s3, s1, 14
	s_sub_i32 s0, s0, s3
	s_cmpk_lt_i32 s0, 4
	s_cbranch_scc0 .Lq_a
	s_lshl_b32 s1, s1, 2
	s_add_i32 s89, s1, s0
	s_addk_i32 s89, 0x80
	s_branch .Lq_done

.Lq_done:
	s_mov_b64 s[6:7], exec
	v_readlane_b32 s0, v254, 7
	v_readlane_b32 s1, v254, 8
	s_and_b64 s[0:1], s[6:7], s[0:1]
	s_mov_b64 exec, s[0:1]
	s_cbranch_execz .LBB0_583
	s_mov_b64 s[10:11], exec
	v_mbcnt_lo_u32_b32 v0, s10, 0
	v_mbcnt_hi_u32_b32 v0, s11, v0
	v_cmp_eq_u32_e32 vcc, 0, v0
	s_and_saveexec_b64 s[8:9], vcc
	s_cbranch_execz .LBB0_582
	s_bcnt1_i32_b64 s0, s[10:11]
	v_mov_b32_e32 v1, s0
	global_atomic_add v253, v73, v1, s[42:43] sc0
.LBB0_582:
	s_or_b64 exec, exec, s[8:9]
.LBB0_583:
	s_or_b64 exec, exec, s[6:7]
	v_mov_b32_e32 v74, v194
	s_mov_b64 s[6:7], -1
	v_readfirstlane_b32 s3, v74
	s_ashr_i32 s86, s3, 6
	v_and_b32_e32 v166, 63, v74
	s_cmpk_gt_i32 s89, 0x7f
	s_cbranch_scc0 .LBB0_663
	s_cmpk_gt_u32 s89, 0x1ff
	s_cbranch_scc0 .LBB0_646
	s_cmpk_gt_u32 s89, 0x3ff
	s_cbranch_scc0 .LBB0_603
	s_add_i32 s2, s89, 0xfffffc00
	s_lshr_b32 s1, s2, 7
	s_mul_i32 s6, s1, 0xab
	s_bfe_u32 s6, s6, 0x70009
	s_mul_i32 s6, s6, 3
	s_sub_i32 s1, s1, s6
	s_and_b32 s1, s1, 0xff
	s_lshl_b32 s16, s1, 1
	s_lshr_b32 s6, 32, s16
	s_and_b32 s17, s89, 31
	s_mul_i32 s2, s2, 0xaaab
	s_add_i32 s6, s6, -1
	s_bfe_u32 s0, s89, 0x20005
	s_lshr_b32 s2, s2, 24
	s_and_b32 s6, s6, s17
	s_cmp_eq_u32 s6, 0
	s_cselect_b64 s[8:9], -1, 0
	s_cmp_lg_u32 s6, 0
	s_mul_i32 s6, s2, 3
	s_cselect_b64 s[10:11], -1, 0
	s_add_i32 s6, s6, s1
	s_lshl_b32 s6, s6, 20
	s_lshl_b32 s7, s0, 18
	s_or_b32 s6, s6, s7
	s_lshl_b32 s18, s6, 1
	s_add_u32 s6, s40, s18
	s_addc_u32 s7, s41, 0
	s_lshl_b32 s12, s17, 14
	s_add_u32 s6, s6, s12
	v_and_b32_e32 v1, 7, v74
	s_addc_u32 s7, s7, 0
	v_lshlrev_b32_e32 v72, 4, v1
	v_lshl_add_u64 v[2:3], s[6:7], 0, v[72:73]
	s_mov_b64 s[12:13], 0x56d2000
	v_lshl_add_u64 v[6:7], v[2:3], 0, s[12:13]
	v_ashrrev_i32_e32 v10, 3, v74
	s_and_b32 s14, s8, 0x4000
	s_add_u32 s20, s6, 0x56d2000
	s_addc_u32 s21, s7, 0
	v_lshlrev_b32_e32 v228, 7, v10
	v_add_u32_e32 v228, v228, v72
	v_lshl_add_u32 v8, v1, 4, 0
	v_add_u32_e32 v229, s14, v228
	v_add_u32_e32 v236, 0x2000, v229
	v_add_u32_e32 v237, 0x4000, v228
	v_add_u32_e32 v238, 0x6000, v228
	global_load_dwordx4 v[196:199], v229, s[20:21]
	global_load_dwordx4 v[200:203], v236, s[20:21]
	global_load_dwordx4 v[204:207], v237, s[20:21]
	global_load_dwordx4 v[208:211], v238, s[20:21]
	v_mad_u64_u32 v[10:11], s[12:13], v10, s79, v[8:9]
	s_lshl_b32 s12, s86, 3
	s_ashr_i32 s13, s12, 31
	s_lshl_b64 s[12:13], s[12:13], 1
	s_add_u32 s6, s6, s12
	s_addc_u32 s7, s7, s13
	s_add_u32 s12, s6, 0x6ed2000
	s_addc_u32 s13, s7, 0
	v_lshlrev_b32_e32 v4, 7, v166
	v_add_u32_e32 v234, s14, v4
	v_add_u32_e32 v239, 0x2000, v234
	v_or_b32_e32 v235, 0x4000, v4
	v_or_b32_e32 v240, 0x6000, v4
	global_load_dwordx4 v[212:215], v234, s[12:13]
	global_load_dwordx4 v[216:219], v239, s[12:13]
	global_load_dwordx4 v[220:223], v235, s[12:13]
	global_load_dwordx4 v[224:227], v240, s[12:13]
	s_mul_i32 s10, s86, 0x1080
	s_add_i32 s10, s10, 0
	v_lshl_add_u32 v12, v166, 1, s10
	s_lshr_b32 s10, 0x1000, s16
	v_readlane_b32 s6, v254, 29
	s_nop 0
	s_add_u32 s12, s6, s18
	v_readlane_b32 s6, v254, 31
	s_nop 0
	s_addc_u32 s13, s6, 0
	s_lshl_b32 s11, s17, 7
	s_lshl_b32 s6, s86, 4
	v_and_b32_e32 v20, 15, v74
	s_add_i32 s7, s6, s11
	v_or_b32_e32 v2, s7, v20
	v_ashrrev_i32_e32 v3, 31, v2
	v_lshlrev_b64 v[2:3], 7, v[2:3]
	v_and_b32_e32 v0, 48, v166
	v_mov_b32_e32 v1, v73
	v_lshl_add_u64 v[2:3], s[12:13], 0, v[2:3]
	v_lshl_add_u64 v[0:1], v[2:3], 0, v[0:1]
	global_load_dwordx4 v[4:7], v[0:1], off
	s_nop 0
	global_load_dwordx4 v[0:3], v[0:1], off offset:64
	s_min_i32 s14, s86, 6
	s_lshl_b32 s7, s14, 4
	v_or_b32_e32 v8, s7, v20
	v_and_b32_e32 v21, 48, v74
	v_mul_lo_u32 v8, v8, s79
	v_add3_u32 v30, 0, v8, v21
	s_add_i32 s21, s7, 16
	v_or_b32_e32 v13, s21, v20
	s_add_i32 s13, s14, 2
	s_lshl_b32 s20, s13, 4
	s_add_i32 s19, s7, 48
	s_add_i32 s12, s14, 4
	s_lshl_b32 s18, s12, 4
	v_or_b32_e32 v26, s18, v20
	v_mul_lo_u32 v26, v26, s79
	v_add3_u32 v42, 0, v26, v21
	s_add_i32 s26, s7, 0x50
	s_add_i32 s15, s14, 6
	s_lshl_b32 s25, s15, 4
	s_add_i32 s24, s7, 0x70
	s_add_i32 s17, s14, 8
	s_lshl_b32 s23, s17, 4
	s_add_i32 s22, s7, 0x90
	s_add_i32 s10, s10, -1
	s_lshl_b32 s70, s2, 12
	s_movk_i32 s2, 0xc00
	s_barrier
	s_waitcnt vmcnt(6)
	s_and_b64 vcc, exec, s[8:9]
	s_cbranch_vccz .Lattn_kz
	v_mov_b32_e32 v196, 0
	v_mov_b32_e32 v197, 0
	v_mov_b32_e32 v198, 0
	v_mov_b32_e32 v199, 0
	v_mov_b32_e32 v200, 0
	v_mov_b32_e32 v201, 0
	v_mov_b32_e32 v202, 0
	v_mov_b32_e32 v203, 0
